# mixprep stage C: RG-LRU gate math of column groups 0-2 regenerated with packed f32 ops over 4 independent elements (same per-element op order), hazard nops gone
# speedup vs baseline: 1.0021x; 1.0021x over previous
.LBB0_317:
	v_add_u32_e32 v182, s4, v0
	ds_read2_b32 v[172:173], v182 offset1:132
	v_add_u32_e32 v176, 0x400, v182
	ds_read2_b32 v[176:177], v176 offset0:8 offset1:140
	s_addk_i32 s4, 0x840
	s_cmpk_eq_i32 s4, 0x2100
	s_waitcnt lgkmcnt(0)
	v_lshlrev_b32_e32 v174, 16, v172
	v_and_b32_e32 v175, 0xffff0000, v172
	v_lshlrev_b32_e32 v172, 16, v173
	v_and_b32_e32 v173, 0xffff0000, v173
	s_waitcnt vmcnt(8)
	v_pk_fma_f32 v[174:175], v[160:161], v[174:175], v[168:169]
	v_lshlrev_b32_e32 v178, 16, v176
	v_and_b32_e32 v179, 0xffff0000, v176
	v_pk_fma_f32 v[174:175], v[162:163], v[172:173], v[174:175]
	v_lshlrev_b32_e32 v176, 16, v177
	v_and_b32_e32 v177, 0xffff0000, v177
	v_pk_fma_f32 v[174:175], v[164:165], v[178:179], v[174:175]
	v_pk_fma_f32 v[172:173], v[160:161], v[172:173], v[168:169]
	v_pk_fma_f32 v[174:175], v[166:167], v[176:177], v[174:175]
	v_pk_fma_f32 v[172:173], v[162:163], v[178:179], v[172:173]
	v_cvt_pk_bf16_f32 v183, v174, v175
	v_add_u32_e32 v174, 0x800, v182
	ds_read2_b32 v[174:175], v174 offset0:16 offset1:148
	v_pk_fma_f32 v[172:173], v[164:165], v[176:177], v[172:173]
	s_waitcnt lgkmcnt(0)
	v_lshlrev_b32_e32 v180, 16, v174
	v_and_b32_e32 v181, 0xffff0000, v174
	v_pk_fma_f32 v[172:173], v[166:167], v[180:181], v[172:173]
	s_nop 0
	v_cvt_pk_bf16_f32 v172, v172, v173
	v_add_u32_e32 v173, 0x8c00, v182
	ds_write2_b32 v173, v183, v172 offset1:132
	v_lshlrev_b32_e32 v172, 16, v175
	v_and_b32_e32 v173, 0xffff0000, v175
	v_pk_fma_f32 v[174:175], v[160:161], v[178:179], v[168:169]
	s_nop 0
	v_pk_fma_f32 v[174:175], v[162:163], v[176:177], v[174:175]
	v_pk_fma_f32 v[176:177], v[160:161], v[176:177], v[168:169]
	v_pk_fma_f32 v[174:175], v[164:165], v[180:181], v[174:175]
	v_pk_fma_f32 v[176:177], v[162:163], v[180:181], v[176:177]
	v_pk_fma_f32 v[174:175], v[166:167], v[172:173], v[174:175]
	v_pk_fma_f32 v[172:173], v[164:165], v[172:173], v[176:177]
	v_cvt_pk_bf16_f32 v178, v174, v175
	ds_read_b32 v175, v182 offset:3168
	s_waitcnt lgkmcnt(0)
	v_lshlrev_b32_e32 v174, 16, v175
	v_and_b32_e32 v175, 0xffff0000, v175
	v_pk_fma_f32 v[172:173], v[166:167], v[174:175], v[172:173]
	s_nop 0
	v_cvt_pk_bf16_f32 v172, v172, v173
	v_add_u32_e32 v173, 0x9000, v182
	ds_write2_b32 v173, v178, v172 offset0:8 offset1:140
	s_cbranch_scc0 .LBB0_317
	s_waitcnt lgkmcnt(0)
	s_barrier
	v_readlane_b32 s5, v252, 45
	v_and_b32_e32 v115, 48, v115
	v_readlane_b32 s6, v252, 51
	v_add_u32_e32 v123, s5, v115
	v_mul_u32_u24_e32 v115, 0x44, v124
	v_lshlrev_b32_e32 v115, 2, v115
	v_readlane_b32 s8, v252, 53
	v_add3_u32 v125, s6, v117, v115
	v_add3_u32 v131, s6, v115, v117
	v_mov_b32_e32 v115, v1
	v_readlane_b32 s9, v252, 54
	s_mov_b32 s4, 0
	v_lshl_add_u32 v0, v116, 3, s5
	s_ashr_i32 s5, s22, 31
	v_lshl_add_u64 v[126:127], s[8:9], 0, v[114:115]
	v_add_u32_e32 v132, s6, v114
	v_mov_b32_e32 v129, 0
	v_mov_b32_e32 v130, 1.0
	s_mov_b32 s100, 0xbfb8aa3b
	s_waitcnt vmcnt(0)
.LBB0_319:
	s_sub_i32 s8, 3, s4
	s_and_b64 s[6:7], s[56:57], exec
	s_cselect_b32 s6, s4, s8
	s_lshl_b32 s6, s6, 4
	v_or_b32_e32 v114, s6, v124
	v_mul_lo_u32 v128, v114, s68
	v_add_u32_e32 v114, v123, v128
	ds_read_b128 v[118:121], v114 offset:35840
	ds_read_b128 v[114:117], v114 offset:35904
	v_add_u32_e32 v128, v0, v128
	ds_read_b64 v[142:143], v128 offset:35840
	s_waitcnt lgkmcnt(0)
	v_mfma_f32_16x16x32_bf16 v[134:137], v[106:109], v[118:121], v[62:65]
	s_add_u32 s6, s6, s22
	s_addc_u32 s7, 0, s5
	s_waitcnt lgkmcnt(0)
	v_lshlrev_b32_e32 v146, 16, v142
	v_mfma_f32_16x16x32_bf16 v[134:137], v[2:5], v[114:117], v[134:137]
	v_and_b32_e32 v147, 0xffff0000, v142
	v_lshlrev_b32_e32 v142, 16, v143
	v_and_b32_e32 v143, 0xffff0000, v143
	v_mfma_f32_16x16x32_bf16 v[138:141], v[30:33], v[118:121], v[90:93]
	s_mov_b32 s8, 12
	s_nop 2
	v_mfma_f32_16x16x32_bf16 v[138:141], v[34:37], v[114:117], v[138:141]
	s_mov_b32 s9, 0
	v_pk_mul_f32 v[134:135], v[134:135], s[100:101] op_sel_hi:[1,0]
	v_pk_mul_f32 v[136:137], v[136:137], s[100:101] op_sel_hi:[1,0]
	v_exp_f32_e32 v134, v134
	v_exp_f32_e32 v135, v135
	v_exp_f32_e32 v136, v136
	v_exp_f32_e32 v137, v137
	v_pk_add_f32 v[134:135], v[134:135], 1.0 op_sel_hi:[1,0]
	v_pk_add_f32 v[136:137], v[136:137], 1.0 op_sel_hi:[1,0]
	v_pk_mul_f32 v[138:139], v[138:139], s[100:101] op_sel_hi:[1,0]
	v_pk_mul_f32 v[140:141], v[140:141], s[100:101] op_sel_hi:[1,0]
	v_rcp_f32_e32 v134, v134
	v_rcp_f32_e32 v135, v135
	v_rcp_f32_e32 v136, v136
	v_rcp_f32_e32 v137, v137
	v_exp_f32_e32 v138, v138
	v_exp_f32_e32 v139, v139
	v_exp_f32_e32 v140, v140
	v_exp_f32_e32 v141, v141
	v_pk_mul_f32 v[148:149], v[98:99], v[134:135]
	v_pk_mul_f32 v[150:151], v[100:101], v[136:137]
	v_pk_add_f32 v[138:139], v[138:139], 1.0 op_sel_hi:[1,0]
	v_pk_add_f32 v[140:141], v[140:141], 1.0 op_sel_hi:[1,0]
	v_exp_f32_e32 v134, v148
	v_exp_f32_e32 v135, v149
	v_exp_f32_e32 v136, v150
	v_exp_f32_e32 v137, v151
	v_rcp_f32_e32 v138, v138
	v_rcp_f32_e32 v139, v139
	v_rcp_f32_e32 v140, v140
	v_rcp_f32_e32 v141, v141
	v_pk_fma_f32 v[148:149], v[134:135], v[134:135], 1.0 op_sel_hi:[1,1,0] neg_lo:[1,0,0] neg_hi:[1,0,0]
	v_pk_fma_f32 v[150:151], v[136:137], v[136:137], 1.0 op_sel_hi:[1,1,0] neg_lo:[1,0,0] neg_hi:[1,0,0]
	v_pk_mul_f32 v[138:139], v[138:139], v[146:147]
	v_pk_mul_f32 v[140:141], v[140:141], v[142:143]
	v_sqrt_f32_e32 v148, v148
	v_sqrt_f32_e32 v149, v149
	v_sqrt_f32_e32 v150, v150
	v_sqrt_f32_e32 v151, v151
	v_pk_mul_f32 v[138:139], v[138:139], v[148:149]
	v_pk_mul_f32 v[140:141], v[140:141], v[150:151]
	ds_write_b128 v125, v[134:137]
	ds_write_b128 v131, v[138:141] offset:4352
	v_mfma_f32_16x16x32_bf16 v[134:137], v[6:9], v[118:121], v[66:69]
	ds_read_b64 v[142:143], v128 offset:35872
	s_waitcnt lgkmcnt(0)
	v_lshlrev_b32_e32 v146, 16, v142
	v_mfma_f32_16x16x32_bf16 v[134:137], v[26:29], v[114:117], v[134:137]
	v_and_b32_e32 v147, 0xffff0000, v142
	v_lshlrev_b32_e32 v142, 16, v143
	v_and_b32_e32 v143, 0xffff0000, v143
	v_mfma_f32_16x16x32_bf16 v[138:141], v[38:41], v[118:121], v[74:77]
	v_mfma_f32_16x16x32_bf16 v[138:141], v[58:61], v[114:117], v[138:141]
	s_nop 2
	v_pk_mul_f32 v[134:135], v[134:135], s[100:101] op_sel_hi:[1,0]
	v_pk_mul_f32 v[136:137], v[136:137], s[100:101] op_sel_hi:[1,0]
	v_exp_f32_e32 v134, v134
	v_exp_f32_e32 v135, v135
	v_exp_f32_e32 v136, v136
	v_exp_f32_e32 v137, v137
	v_pk_add_f32 v[134:135], v[134:135], 1.0 op_sel_hi:[1,0]
	v_pk_add_f32 v[136:137], v[136:137], 1.0 op_sel_hi:[1,0]
	v_pk_mul_f32 v[138:139], v[138:139], s[100:101] op_sel_hi:[1,0]
	v_pk_mul_f32 v[140:141], v[140:141], s[100:101] op_sel_hi:[1,0]
	v_rcp_f32_e32 v134, v134
	v_rcp_f32_e32 v135, v135
	v_rcp_f32_e32 v136, v136
	v_rcp_f32_e32 v137, v137
	v_exp_f32_e32 v138, v138
	v_exp_f32_e32 v139, v139
	v_exp_f32_e32 v140, v140
	v_exp_f32_e32 v141, v141
	v_pk_mul_f32 v[148:149], v[82:83], v[134:135]
	v_pk_mul_f32 v[150:151], v[84:85], v[136:137]
	v_pk_add_f32 v[138:139], v[138:139], 1.0 op_sel_hi:[1,0]
	v_pk_add_f32 v[140:141], v[140:141], 1.0 op_sel_hi:[1,0]
	v_exp_f32_e32 v134, v148
	v_exp_f32_e32 v135, v149
	v_exp_f32_e32 v136, v150
	v_exp_f32_e32 v137, v151
	v_rcp_f32_e32 v138, v138
	v_rcp_f32_e32 v139, v139
	v_rcp_f32_e32 v140, v140
	v_rcp_f32_e32 v141, v141
	v_pk_fma_f32 v[148:149], v[134:135], v[134:135], 1.0 op_sel_hi:[1,1,0] neg_lo:[1,0,0] neg_hi:[1,0,0]
	v_pk_fma_f32 v[150:151], v[136:137], v[136:137], 1.0 op_sel_hi:[1,1,0] neg_lo:[1,0,0] neg_hi:[1,0,0]
	v_pk_mul_f32 v[138:139], v[138:139], v[146:147]
	v_pk_mul_f32 v[140:141], v[140:141], v[142:143]
	v_sqrt_f32_e32 v148, v148
	v_sqrt_f32_e32 v149, v149
	v_sqrt_f32_e32 v150, v150
	v_sqrt_f32_e32 v151, v151
	v_pk_mul_f32 v[138:139], v[138:139], v[148:149]
	v_pk_mul_f32 v[140:141], v[140:141], v[150:151]
	ds_write_b128 v125, v[134:137] offset:64
	ds_write_b128 v131, v[138:141] offset:4416
	v_mfma_f32_16x16x32_bf16 v[134:137], v[10:13], v[118:121], v[70:73]
	ds_read_b64 v[142:143], v128 offset:35904
	s_waitcnt lgkmcnt(0)
	v_lshlrev_b32_e32 v146, 16, v142
	v_mfma_f32_16x16x32_bf16 v[134:137], v[14:17], v[114:117], v[134:137]
	v_and_b32_e32 v147, 0xffff0000, v142
	v_lshlrev_b32_e32 v142, 16, v143
	v_and_b32_e32 v143, 0xffff0000, v143
	v_mfma_f32_16x16x32_bf16 v[138:141], v[42:45], v[118:121], v[78:81]
	v_mfma_f32_16x16x32_bf16 v[138:141], v[46:49], v[114:117], v[138:141]
	s_nop 2
	v_pk_mul_f32 v[134:135], v[134:135], s[100:101] op_sel_hi:[1,0]
	v_pk_mul_f32 v[136:137], v[136:137], s[100:101] op_sel_hi:[1,0]
	v_exp_f32_e32 v134, v134
	v_exp_f32_e32 v135, v135
	v_exp_f32_e32 v136, v136
	v_exp_f32_e32 v137, v137
	v_pk_add_f32 v[134:135], v[134:135], 1.0 op_sel_hi:[1,0]
	v_pk_add_f32 v[136:137], v[136:137], 1.0 op_sel_hi:[1,0]
	v_pk_mul_f32 v[138:139], v[138:139], s[100:101] op_sel_hi:[1,0]
	v_pk_mul_f32 v[140:141], v[140:141], s[100:101] op_sel_hi:[1,0]
	v_rcp_f32_e32 v134, v134
	v_rcp_f32_e32 v135, v135
	v_rcp_f32_e32 v136, v136
	v_rcp_f32_e32 v137, v137
	v_exp_f32_e32 v138, v138
	v_exp_f32_e32 v139, v139
	v_exp_f32_e32 v140, v140
	v_exp_f32_e32 v141, v141
	v_pk_mul_f32 v[148:149], v[86:87], v[134:135]
	v_pk_mul_f32 v[150:151], v[88:89], v[136:137]
	v_pk_add_f32 v[138:139], v[138:139], 1.0 op_sel_hi:[1,0]
	v_pk_add_f32 v[140:141], v[140:141], 1.0 op_sel_hi:[1,0]
	v_exp_f32_e32 v134, v148
	v_exp_f32_e32 v135, v149
	v_exp_f32_e32 v136, v150
	v_exp_f32_e32 v137, v151
	v_rcp_f32_e32 v138, v138
	v_rcp_f32_e32 v139, v139
	v_rcp_f32_e32 v140, v140
	v_rcp_f32_e32 v141, v141
	v_pk_fma_f32 v[148:149], v[134:135], v[134:135], 1.0 op_sel_hi:[1,1,0] neg_lo:[1,0,0] neg_hi:[1,0,0]
	v_pk_fma_f32 v[150:151], v[136:137], v[136:137], 1.0 op_sel_hi:[1,1,0] neg_lo:[1,0,0] neg_hi:[1,0,0]
	v_pk_mul_f32 v[138:139], v[138:139], v[146:147]
	v_pk_mul_f32 v[140:141], v[140:141], v[142:143]
	v_sqrt_f32_e32 v148, v148
	v_sqrt_f32_e32 v149, v149
	v_sqrt_f32_e32 v150, v150
	v_sqrt_f32_e32 v151, v151
	v_pk_mul_f32 v[138:139], v[138:139], v[148:149]
	v_pk_mul_f32 v[140:141], v[140:141], v[150:151]
	ds_write_b128 v125, v[134:137] offset:128
	ds_write_b128 v131, v[138:141] offset:4480
	v_mfma_f32_16x16x32_bf16 v[134:137], v[18:21], v[118:121], v[94:97]
	v_mfma_f32_16x16x32_bf16 v[134:137], v[22:25], v[114:117], v[134:137]
	v_mfma_f32_16x16x32_bf16 v[118:121], v[50:53], v[118:121], v[102:105]
	v_mfma_f32_16x16x32_bf16 v[114:117], v[54:57], v[114:117], v[118:121]
	s_nop 6
	v_mul_f32_e32 v118, 0xbfb8aa3b, v134
	v_exp_f32_e32 v118, v118
	v_mul_f32_e32 v114, 0xbfb8aa3b, v114
	v_exp_f32_e32 v114, v114
	v_mul_f32_e32 v115, 0xbfb8aa3b, v115
	v_add_f32_e32 v118, 1.0, v118
	v_rcp_f32_e32 v119, v118
	v_add_f32_e32 v114, 1.0, v114
	v_rcp_f32_e32 v118, v114
	ds_read_b64 v[120:121], v128 offset:35936
	v_mul_f32_e32 v114, v110, v119
	v_exp_f32_e32 v114, v114
	v_exp_f32_e32 v115, v115
	v_mul_f32_e32 v116, 0xbfb8aa3b, v116
	s_waitcnt lgkmcnt(0)
	v_lshlrev_b32_e32 v138, 16, v120
	v_fma_f32 v119, -v114, v114, 1.0
	v_sqrt_f32_e32 v134, v119
	v_mul_f32_e32 v119, 0xbfb8aa3b, v135
	v_exp_f32_e32 v119, v119
	v_add_f32_e32 v115, 1.0, v115
	v_and_b32_e32 v139, 0xffff0000, v120
	v_mul_f32_e32 v120, 0xbfb8aa3b, v136
	v_add_f32_e32 v119, 1.0, v119
	v_rcp_f32_e32 v128, v119
	v_rcp_f32_e32 v119, v115
	v_exp_f32_e32 v120, v120
	v_exp_f32_e32 v116, v116
	v_mul_f32_e32 v115, v111, v128
	v_exp_f32_e32 v115, v115
	v_add_f32_e32 v120, 1.0, v120
	v_rcp_f32_e32 v120, v120
	v_pk_mul_f32 v[118:119], v[118:119], v[138:139]
	v_fma_f32 v128, -v115, v115, 1.0
	v_sqrt_f32_e32 v135, v128
	v_add_f32_e32 v116, 1.0, v116
	v_mul_f32_e32 v117, 0xbfb8aa3b, v117
	v_exp_f32_e32 v117, v117
	v_pk_mul_f32 v[118:119], v[118:119], v[134:135]
	v_rcp_f32_e32 v134, v116
	v_mul_f32_e32 v116, v112, v120
	v_exp_f32_e32 v116, v116
	v_add_f32_e32 v117, 1.0, v117
	v_rcp_f32_e32 v135, v117
	v_fma_f32 v120, -v116, v116, 1.0
	v_sqrt_f32_e32 v136, v120
	v_mul_f32_e32 v120, 0xbfb8aa3b, v137
	v_exp_f32_e32 v120, v120
	s_nop 0
	v_add_f32_e32 v120, 1.0, v120
	v_rcp_f32_e32 v120, v120
	s_nop 0
	v_mul_f32_e32 v117, v113, v120
	v_exp_f32_e32 v117, v117
	s_nop 0
	v_fma_f32 v120, -v117, v117, 1.0
	v_sqrt_f32_e32 v137, v120
	v_lshlrev_b32_e32 v120, 16, v121
	v_and_b32_e32 v121, 0xffff0000, v121
	v_pk_mul_f32 v[120:121], v[134:135], v[120:121]
	s_nop 0
	v_pk_mul_f32 v[120:121], v[120:121], v[136:137]
	ds_write_b128 v125, v[114:117] offset:192
	ds_write_b128 v131, v[118:121] offset:4544
	s_waitcnt lgkmcnt(0)
